# M1 S5 pass-1 B.u products on f32 MFMA (v_mfma_f32_16x16x4_f32, 16-token blocks via LDS) + 2-pk complex recurrence
# speedup vs baseline: 1.0144x; 1.0015x over previous
.LBB0_505:
	v_mbcnt_lo_u32_b32 v140, -1, 0
	v_mbcnt_hi_u32_b32 v140, -1, v140
	s_and_b32 s11, s38, 7
	s_lshl_b32 s11, s11, 13
	s_add_i32 s11, s11, 0x10000
	v_and_b32_e32 v196, 15, v140
	v_lshrrev_b32_e32 v197, 4, v140
	v_bfe_u32 v198, v140, 1, 3
	v_lshlrev_b32_e32 v141, 7, v140
	v_lshl_or_b32 v141, v198, 4, v141
	v_add_u32_e32 v141, s11, v141
	v_xor_b32_e32 v245, 16, v141
	v_xor_b32_e32 v246, 32, v141
	v_xor_b32_e32 v247, 48, v141
	v_xor_b32_e32 v248, 64, v141
	v_xor_b32_e32 v249, 80, v141
	v_xor_b32_e32 v250, 96, v141
	v_xor_b32_e32 v251, 112, v141
	ds_write_b64 v141, v[30:31]
	ds_write_b64 v141, v[38:39] offset:8
	ds_write_b64 v245, v[40:41]
	ds_write_b64 v245, v[42:43] offset:8
	ds_write_b64 v246, v[44:45]
	ds_write_b64 v246, v[46:47] offset:8
	ds_write_b64 v247, v[48:49]
	ds_write_b64 v247, v[50:51] offset:8
	ds_write_b64 v248, v[52:53]
	ds_write_b64 v248, v[54:55] offset:8
	ds_write_b64 v249, v[56:57]
	ds_write_b64 v249, v[58:59] offset:8
	ds_write_b64 v250, v[60:61]
	ds_write_b64 v250, v[62:63] offset:8
	ds_write_b64 v251, v[64:65]
	ds_write_b64 v251, v[66:67] offset:8
	v_bfe_u32 v198, v196, 1, 3
	v_lshlrev_b32_e32 v199, 1, v197
	v_xor_b32_e32 v199, v199, v198
	v_lshlrev_b32_e32 v142, 7, v196
	v_lshl_or_b32 v142, v199, 4, v142
	v_add_u32_e32 v142, s11, v142
	v_xor_b32_e32 v143, 16, v142
	ds_read_b128 v[160:163], v142
	ds_read_b128 v[164:167], v143
	ds_read_b128 v[168:171], v142 offset:2048
	ds_read_b128 v[172:175], v143 offset:2048
	ds_read_b128 v[176:179], v142 offset:4096
	ds_read_b128 v[180:183], v143 offset:4096
	ds_read_b128 v[184:187], v142 offset:6144
	ds_read_b128 v[188:191], v143 offset:6144
	v_lshlrev_b32_e32 v144, 10, v196
	v_lshl_add_u32 v144, v197, 4, v144
	v_add_u32_e32 v144, s10, v144
	ds_read_b128 v[154:157], v144
	ds_read_b128 v[192:195], v144 offset:16384
	v_lshlrev_b32_e32 v198, 11, v197
	v_lshl_add_u32 v198, v196, 2, v198
	v_add_u32_e32 v198, s11, v198
	v_mov_b32_e32 v199, v197
	v_lshl_add_u32 v145, v199, 6, v198
	v_xor_b32_e32 v199, 1, v197
	v_lshl_add_u32 v146, v199, 6, v198
	v_xor_b32_e32 v199, 2, v197
	v_lshl_add_u32 v147, v199, 6, v198
	v_xor_b32_e32 v199, 3, v197
	v_lshl_add_u32 v148, v199, 6, v198
	v_lshlrev_b32_e32 v198, 2, v140
	v_add_u32_e32 v149, s11, v198
	v_xor_b32_e32 v199, 64, v198
	v_add_u32_e32 v150, s11, v199
	v_xor_b32_e32 v199, 128, v198
	v_add_u32_e32 v151, s11, v199
	v_xor_b32_e32 v199, 192, v198
	v_add_u32_e32 v152, s11, v199
	s_waitcnt lgkmcnt(0)
	v_mfma_f32_16x16x4_f32 v[212:215], v154, v160, 0
	v_mfma_f32_16x16x4_f32 v[216:219], v154, v161, 0
	v_mfma_f32_16x16x4_f32 v[220:223], v154, v168, 0
	v_mfma_f32_16x16x4_f32 v[224:227], v154, v169, 0
	v_mfma_f32_16x16x4_f32 v[228:231], v154, v176, 0
	v_mfma_f32_16x16x4_f32 v[232:235], v154, v177, 0
	v_mfma_f32_16x16x4_f32 v[236:239], v154, v184, 0
	v_mfma_f32_16x16x4_f32 v[240:243], v154, v185, 0
	v_mfma_f32_16x16x4_f32 v[212:215], v155, v162, v[212:215]
	v_mfma_f32_16x16x4_f32 v[216:219], v155, v163, v[216:219]
	v_mfma_f32_16x16x4_f32 v[220:223], v155, v170, v[220:223]
	v_mfma_f32_16x16x4_f32 v[224:227], v155, v171, v[224:227]
	v_mfma_f32_16x16x4_f32 v[228:231], v155, v178, v[228:231]
	v_mfma_f32_16x16x4_f32 v[232:235], v155, v179, v[232:235]
	v_mfma_f32_16x16x4_f32 v[236:239], v155, v186, v[236:239]
	v_mfma_f32_16x16x4_f32 v[240:243], v155, v187, v[240:243]
	v_mfma_f32_16x16x4_f32 v[212:215], v156, v164, v[212:215]
	v_mfma_f32_16x16x4_f32 v[216:219], v156, v165, v[216:219]
	v_mfma_f32_16x16x4_f32 v[220:223], v156, v172, v[220:223]
	v_mfma_f32_16x16x4_f32 v[224:227], v156, v173, v[224:227]
	v_mfma_f32_16x16x4_f32 v[228:231], v156, v180, v[228:231]
	v_mfma_f32_16x16x4_f32 v[232:235], v156, v181, v[232:235]
	v_mfma_f32_16x16x4_f32 v[236:239], v156, v188, v[236:239]
	v_mfma_f32_16x16x4_f32 v[240:243], v156, v189, v[240:243]
	v_mfma_f32_16x16x4_f32 v[212:215], v157, v166, v[212:215]
	v_mfma_f32_16x16x4_f32 v[216:219], v157, v167, v[216:219]
	v_mfma_f32_16x16x4_f32 v[220:223], v157, v174, v[220:223]
	v_mfma_f32_16x16x4_f32 v[224:227], v157, v175, v[224:227]
	v_mfma_f32_16x16x4_f32 v[228:231], v157, v182, v[228:231]
	v_mfma_f32_16x16x4_f32 v[232:235], v157, v183, v[232:235]
	v_mfma_f32_16x16x4_f32 v[236:239], v157, v190, v[236:239]
	v_mfma_f32_16x16x4_f32 v[240:243], v157, v191, v[240:243]
	s_nop 9
	ds_write_b32 v145, v212
	ds_write_b32 v145, v213 offset:512
	ds_write_b32 v145, v214 offset:1024
	ds_write_b32 v145, v215 offset:1536
	ds_write_b32 v145, v216 offset:256
	ds_write_b32 v145, v217 offset:768
	ds_write_b32 v145, v218 offset:1280
	ds_write_b32 v145, v219 offset:1792
	ds_write_b32 v146, v220
	ds_write_b32 v146, v221 offset:512
	ds_write_b32 v146, v222 offset:1024
	ds_write_b32 v146, v223 offset:1536
	ds_write_b32 v146, v224 offset:256
	ds_write_b32 v146, v225 offset:768
	ds_write_b32 v146, v226 offset:1280
	ds_write_b32 v146, v227 offset:1792
	ds_write_b32 v147, v228
	ds_write_b32 v147, v229 offset:512
	ds_write_b32 v147, v230 offset:1024
	ds_write_b32 v147, v231 offset:1536
	ds_write_b32 v147, v232 offset:256
	ds_write_b32 v147, v233 offset:768
	ds_write_b32 v147, v234 offset:1280
	ds_write_b32 v147, v235 offset:1792
	ds_write_b32 v148, v236
	ds_write_b32 v148, v237 offset:512
	ds_write_b32 v148, v238 offset:1024
	ds_write_b32 v148, v239 offset:1536
	ds_write_b32 v148, v240 offset:256
	ds_write_b32 v148, v241 offset:768
	ds_write_b32 v148, v242 offset:1280
	ds_write_b32 v148, v243 offset:1792
	ds_read_b32 v196, v149
	ds_read_b32 v197, v149 offset:256
	ds_read_b32 v198, v149 offset:512
	ds_read_b32 v199, v149 offset:768
	ds_read_b32 v200, v149 offset:1024
	ds_read_b32 v201, v149 offset:1280
	ds_read_b32 v202, v149 offset:1536
	ds_read_b32 v203, v149 offset:1792
	ds_read_b32 v244, v150 offset:2048
	ds_read_b32 v245, v150 offset:2304
	ds_read_b32 v246, v150 offset:2560
	ds_read_b32 v247, v150 offset:2816
	ds_read_b32 v248, v150 offset:3072
	ds_read_b32 v249, v150 offset:3328
	ds_read_b32 v250, v150 offset:3584
	ds_read_b32 v251, v150 offset:3840
	s_waitcnt lgkmcnt(8)
	v_pk_fma_f32 v[252:253], v[34:35], v[36:37], v[196:197] op_sel:[0,1,0] op_sel_hi:[1,0,1] neg_lo:[1,0,0] neg_hi:[0,0,0]
	v_mfma_f32_16x16x4_f32 v[212:215], v192, v160, 0
	v_pk_fma_f32 v[36:37], v[32:33], v[36:37], v[252:253]
	v_mfma_f32_16x16x4_f32 v[216:219], v192, v161, 0
	v_pk_fma_f32 v[252:253], v[34:35], v[36:37], v[198:199] op_sel:[0,1,0] op_sel_hi:[1,0,1] neg_lo:[1,0,0] neg_hi:[0,0,0]
	v_mfma_f32_16x16x4_f32 v[220:223], v192, v168, 0
	v_pk_fma_f32 v[36:37], v[32:33], v[36:37], v[252:253]
	v_mfma_f32_16x16x4_f32 v[224:227], v192, v169, 0
	v_pk_fma_f32 v[252:253], v[34:35], v[36:37], v[200:201] op_sel:[0,1,0] op_sel_hi:[1,0,1] neg_lo:[1,0,0] neg_hi:[0,0,0]
	v_mfma_f32_16x16x4_f32 v[228:231], v192, v176, 0
	v_pk_fma_f32 v[36:37], v[32:33], v[36:37], v[252:253]
	v_mfma_f32_16x16x4_f32 v[232:235], v192, v177, 0
	v_pk_fma_f32 v[252:253], v[34:35], v[36:37], v[202:203] op_sel:[0,1,0] op_sel_hi:[1,0,1] neg_lo:[1,0,0] neg_hi:[0,0,0]
	v_mfma_f32_16x16x4_f32 v[236:239], v192, v184, 0
	v_pk_fma_f32 v[36:37], v[32:33], v[36:37], v[252:253]
	v_mfma_f32_16x16x4_f32 v[240:243], v192, v185, 0
	ds_read_b32 v196, v151 offset:4096
	ds_read_b32 v197, v151 offset:4352
	ds_read_b32 v198, v151 offset:4608
	ds_read_b32 v199, v151 offset:4864
	ds_read_b32 v200, v151 offset:5120
	ds_read_b32 v201, v151 offset:5376
	ds_read_b32 v202, v151 offset:5632
	ds_read_b32 v203, v151 offset:5888
	s_waitcnt lgkmcnt(8)
	v_pk_fma_f32 v[252:253], v[34:35], v[36:37], v[244:245] op_sel:[0,1,0] op_sel_hi:[1,0,1] neg_lo:[1,0,0] neg_hi:[0,0,0]
	v_mfma_f32_16x16x4_f32 v[212:215], v193, v162, v[212:215]
	v_pk_fma_f32 v[36:37], v[32:33], v[36:37], v[252:253]
	v_mfma_f32_16x16x4_f32 v[216:219], v193, v163, v[216:219]
	v_pk_fma_f32 v[252:253], v[34:35], v[36:37], v[246:247] op_sel:[0,1,0] op_sel_hi:[1,0,1] neg_lo:[1,0,0] neg_hi:[0,0,0]
	v_mfma_f32_16x16x4_f32 v[220:223], v193, v170, v[220:223]
	v_pk_fma_f32 v[36:37], v[32:33], v[36:37], v[252:253]
	v_mfma_f32_16x16x4_f32 v[224:227], v193, v171, v[224:227]
	v_pk_fma_f32 v[252:253], v[34:35], v[36:37], v[248:249] op_sel:[0,1,0] op_sel_hi:[1,0,1] neg_lo:[1,0,0] neg_hi:[0,0,0]
	v_mfma_f32_16x16x4_f32 v[228:231], v193, v178, v[228:231]
	v_pk_fma_f32 v[36:37], v[32:33], v[36:37], v[252:253]
	v_mfma_f32_16x16x4_f32 v[232:235], v193, v179, v[232:235]
	v_pk_fma_f32 v[252:253], v[34:35], v[36:37], v[250:251] op_sel:[0,1,0] op_sel_hi:[1,0,1] neg_lo:[1,0,0] neg_hi:[0,0,0]
	v_mfma_f32_16x16x4_f32 v[236:239], v193, v186, v[236:239]
	v_pk_fma_f32 v[36:37], v[32:33], v[36:37], v[252:253]
	v_mfma_f32_16x16x4_f32 v[240:243], v193, v187, v[240:243]
	ds_read_b32 v244, v152 offset:6144
	ds_read_b32 v245, v152 offset:6400
	ds_read_b32 v246, v152 offset:6656
	ds_read_b32 v247, v152 offset:6912
	ds_read_b32 v248, v152 offset:7168
	ds_read_b32 v249, v152 offset:7424
	ds_read_b32 v250, v152 offset:7680
	ds_read_b32 v251, v152 offset:7936
	s_waitcnt lgkmcnt(8)
	v_pk_fma_f32 v[252:253], v[34:35], v[36:37], v[196:197] op_sel:[0,1,0] op_sel_hi:[1,0,1] neg_lo:[1,0,0] neg_hi:[0,0,0]
	v_mfma_f32_16x16x4_f32 v[212:215], v194, v164, v[212:215]
	v_pk_fma_f32 v[36:37], v[32:33], v[36:37], v[252:253]
	v_mfma_f32_16x16x4_f32 v[216:219], v194, v165, v[216:219]
	v_pk_fma_f32 v[252:253], v[34:35], v[36:37], v[198:199] op_sel:[0,1,0] op_sel_hi:[1,0,1] neg_lo:[1,0,0] neg_hi:[0,0,0]
	v_mfma_f32_16x16x4_f32 v[220:223], v194, v172, v[220:223]
	v_pk_fma_f32 v[36:37], v[32:33], v[36:37], v[252:253]
	v_mfma_f32_16x16x4_f32 v[224:227], v194, v173, v[224:227]
	v_pk_fma_f32 v[252:253], v[34:35], v[36:37], v[200:201] op_sel:[0,1,0] op_sel_hi:[1,0,1] neg_lo:[1,0,0] neg_hi:[0,0,0]
	v_mfma_f32_16x16x4_f32 v[228:231], v194, v180, v[228:231]
	v_pk_fma_f32 v[36:37], v[32:33], v[36:37], v[252:253]
	v_mfma_f32_16x16x4_f32 v[232:235], v194, v181, v[232:235]
	v_pk_fma_f32 v[252:253], v[34:35], v[36:37], v[202:203] op_sel:[0,1,0] op_sel_hi:[1,0,1] neg_lo:[1,0,0] neg_hi:[0,0,0]
	v_mfma_f32_16x16x4_f32 v[236:239], v194, v188, v[236:239]
	v_pk_fma_f32 v[36:37], v[32:33], v[36:37], v[252:253]
	v_mfma_f32_16x16x4_f32 v[240:243], v194, v189, v[240:243]
	ds_read_b128 v[154:157], v144 offset:32768
	s_waitcnt lgkmcnt(1)
	v_pk_fma_f32 v[252:253], v[34:35], v[36:37], v[244:245] op_sel:[0,1,0] op_sel_hi:[1,0,1] neg_lo:[1,0,0] neg_hi:[0,0,0]
	v_mfma_f32_16x16x4_f32 v[212:215], v195, v166, v[212:215]
	v_pk_fma_f32 v[36:37], v[32:33], v[36:37], v[252:253]
	v_mfma_f32_16x16x4_f32 v[216:219], v195, v167, v[216:219]
	v_pk_fma_f32 v[252:253], v[34:35], v[36:37], v[246:247] op_sel:[0,1,0] op_sel_hi:[1,0,1] neg_lo:[1,0,0] neg_hi:[0,0,0]
	v_mfma_f32_16x16x4_f32 v[220:223], v195, v174, v[220:223]
	v_pk_fma_f32 v[36:37], v[32:33], v[36:37], v[252:253]
	v_mfma_f32_16x16x4_f32 v[224:227], v195, v175, v[224:227]
	v_pk_fma_f32 v[252:253], v[34:35], v[36:37], v[248:249] op_sel:[0,1,0] op_sel_hi:[1,0,1] neg_lo:[1,0,0] neg_hi:[0,0,0]
	v_mfma_f32_16x16x4_f32 v[228:231], v195, v182, v[228:231]
	v_pk_fma_f32 v[36:37], v[32:33], v[36:37], v[252:253]
	v_mfma_f32_16x16x4_f32 v[232:235], v195, v183, v[232:235]
	v_pk_fma_f32 v[252:253], v[34:35], v[36:37], v[250:251] op_sel:[0,1,0] op_sel_hi:[1,0,1] neg_lo:[1,0,0] neg_hi:[0,0,0]
	v_mfma_f32_16x16x4_f32 v[236:239], v195, v190, v[236:239]
	v_pk_fma_f32 v[36:37], v[32:33], v[36:37], v[252:253]
	v_mfma_f32_16x16x4_f32 v[240:243], v195, v191, v[240:243]
	s_nop 9
	ds_write_b32 v145, v212
	ds_write_b32 v145, v213 offset:512
	ds_write_b32 v145, v214 offset:1024
	ds_write_b32 v145, v215 offset:1536
	ds_write_b32 v145, v216 offset:256
	ds_write_b32 v145, v217 offset:768
	ds_write_b32 v145, v218 offset:1280
	ds_write_b32 v145, v219 offset:1792
	ds_write_b32 v146, v220
	ds_write_b32 v146, v221 offset:512
	ds_write_b32 v146, v222 offset:1024
	ds_write_b32 v146, v223 offset:1536
	ds_write_b32 v146, v224 offset:256
	ds_write_b32 v146, v225 offset:768
	ds_write_b32 v146, v226 offset:1280
	ds_write_b32 v146, v227 offset:1792
	ds_write_b32 v147, v228
	ds_write_b32 v147, v229 offset:512
	ds_write_b32 v147, v230 offset:1024
	ds_write_b32 v147, v231 offset:1536
	ds_write_b32 v147, v232 offset:256
	ds_write_b32 v147, v233 offset:768
	ds_write_b32 v147, v234 offset:1280
	ds_write_b32 v147, v235 offset:1792
	ds_write_b32 v148, v236
	ds_write_b32 v148, v237 offset:512
	ds_write_b32 v148, v238 offset:1024
	ds_write_b32 v148, v239 offset:1536
	ds_write_b32 v148, v240 offset:256
	ds_write_b32 v148, v241 offset:768
	ds_write_b32 v148, v242 offset:1280
	ds_write_b32 v148, v243 offset:1792
	ds_read_b32 v196, v149
	ds_read_b32 v197, v149 offset:256
	ds_read_b32 v198, v149 offset:512
	ds_read_b32 v199, v149 offset:768
	ds_read_b32 v200, v149 offset:1024
	ds_read_b32 v201, v149 offset:1280
	ds_read_b32 v202, v149 offset:1536
	ds_read_b32 v203, v149 offset:1792
	ds_read_b32 v244, v150 offset:2048
	ds_read_b32 v245, v150 offset:2304
	ds_read_b32 v246, v150 offset:2560
	ds_read_b32 v247, v150 offset:2816
	ds_read_b32 v248, v150 offset:3072
	ds_read_b32 v249, v150 offset:3328
	ds_read_b32 v250, v150 offset:3584
	ds_read_b32 v251, v150 offset:3840
	s_waitcnt lgkmcnt(8)
	v_pk_fma_f32 v[252:253], v[34:35], v[36:37], v[196:197] op_sel:[0,1,0] op_sel_hi:[1,0,1] neg_lo:[1,0,0] neg_hi:[0,0,0]
	v_mfma_f32_16x16x4_f32 v[212:215], v154, v160, 0
	v_pk_fma_f32 v[36:37], v[32:33], v[36:37], v[252:253]
	v_mfma_f32_16x16x4_f32 v[216:219], v154, v161, 0
	v_pk_fma_f32 v[252:253], v[34:35], v[36:37], v[198:199] op_sel:[0,1,0] op_sel_hi:[1,0,1] neg_lo:[1,0,0] neg_hi:[0,0,0]
	v_mfma_f32_16x16x4_f32 v[220:223], v154, v168, 0
	v_pk_fma_f32 v[36:37], v[32:33], v[36:37], v[252:253]
	v_mfma_f32_16x16x4_f32 v[224:227], v154, v169, 0
	v_pk_fma_f32 v[252:253], v[34:35], v[36:37], v[200:201] op_sel:[0,1,0] op_sel_hi:[1,0,1] neg_lo:[1,0,0] neg_hi:[0,0,0]
	v_mfma_f32_16x16x4_f32 v[228:231], v154, v176, 0
	v_pk_fma_f32 v[36:37], v[32:33], v[36:37], v[252:253]
	v_mfma_f32_16x16x4_f32 v[232:235], v154, v177, 0
	v_pk_fma_f32 v[252:253], v[34:35], v[36:37], v[202:203] op_sel:[0,1,0] op_sel_hi:[1,0,1] neg_lo:[1,0,0] neg_hi:[0,0,0]
	v_mfma_f32_16x16x4_f32 v[236:239], v154, v184, 0
	v_pk_fma_f32 v[36:37], v[32:33], v[36:37], v[252:253]
	v_mfma_f32_16x16x4_f32 v[240:243], v154, v185, 0
	ds_read_b32 v196, v151 offset:4096
	ds_read_b32 v197, v151 offset:4352
	ds_read_b32 v198, v151 offset:4608
	ds_read_b32 v199, v151 offset:4864
	ds_read_b32 v200, v151 offset:5120
	ds_read_b32 v201, v151 offset:5376
	ds_read_b32 v202, v151 offset:5632
	ds_read_b32 v203, v151 offset:5888
	s_waitcnt lgkmcnt(8)
	v_pk_fma_f32 v[252:253], v[34:35], v[36:37], v[244:245] op_sel:[0,1,0] op_sel_hi:[1,0,1] neg_lo:[1,0,0] neg_hi:[0,0,0]
	v_mfma_f32_16x16x4_f32 v[212:215], v155, v162, v[212:215]
	v_pk_fma_f32 v[36:37], v[32:33], v[36:37], v[252:253]
	v_mfma_f32_16x16x4_f32 v[216:219], v155, v163, v[216:219]
	v_pk_fma_f32 v[252:253], v[34:35], v[36:37], v[246:247] op_sel:[0,1,0] op_sel_hi:[1,0,1] neg_lo:[1,0,0] neg_hi:[0,0,0]
	v_mfma_f32_16x16x4_f32 v[220:223], v155, v170, v[220:223]
	v_pk_fma_f32 v[36:37], v[32:33], v[36:37], v[252:253]
	v_mfma_f32_16x16x4_f32 v[224:227], v155, v171, v[224:227]
	v_pk_fma_f32 v[252:253], v[34:35], v[36:37], v[248:249] op_sel:[0,1,0] op_sel_hi:[1,0,1] neg_lo:[1,0,0] neg_hi:[0,0,0]
	v_mfma_f32_16x16x4_f32 v[228:231], v155, v178, v[228:231]
	v_pk_fma_f32 v[36:37], v[32:33], v[36:37], v[252:253]
	v_mfma_f32_16x16x4_f32 v[232:235], v155, v179, v[232:235]
	v_pk_fma_f32 v[252:253], v[34:35], v[36:37], v[250:251] op_sel:[0,1,0] op_sel_hi:[1,0,1] neg_lo:[1,0,0] neg_hi:[0,0,0]
	v_mfma_f32_16x16x4_f32 v[236:239], v155, v186, v[236:239]
	v_pk_fma_f32 v[36:37], v[32:33], v[36:37], v[252:253]
	v_mfma_f32_16x16x4_f32 v[240:243], v155, v187, v[240:243]
	ds_read_b32 v244, v152 offset:6144
	ds_read_b32 v245, v152 offset:6400
	ds_read_b32 v246, v152 offset:6656
	ds_read_b32 v247, v152 offset:6912
	ds_read_b32 v248, v152 offset:7168
	ds_read_b32 v249, v152 offset:7424
	ds_read_b32 v250, v152 offset:7680
	ds_read_b32 v251, v152 offset:7936
	s_waitcnt lgkmcnt(8)
	v_pk_fma_f32 v[252:253], v[34:35], v[36:37], v[196:197] op_sel:[0,1,0] op_sel_hi:[1,0,1] neg_lo:[1,0,0] neg_hi:[0,0,0]
	v_mfma_f32_16x16x4_f32 v[212:215], v156, v164, v[212:215]
	v_pk_fma_f32 v[36:37], v[32:33], v[36:37], v[252:253]
	v_mfma_f32_16x16x4_f32 v[216:219], v156, v165, v[216:219]
	v_pk_fma_f32 v[252:253], v[34:35], v[36:37], v[198:199] op_sel:[0,1,0] op_sel_hi:[1,0,1] neg_lo:[1,0,0] neg_hi:[0,0,0]
	v_mfma_f32_16x16x4_f32 v[220:223], v156, v172, v[220:223]
	v_pk_fma_f32 v[36:37], v[32:33], v[36:37], v[252:253]
	v_mfma_f32_16x16x4_f32 v[224:227], v156, v173, v[224:227]
	v_pk_fma_f32 v[252:253], v[34:35], v[36:37], v[200:201] op_sel:[0,1,0] op_sel_hi:[1,0,1] neg_lo:[1,0,0] neg_hi:[0,0,0]
	v_mfma_f32_16x16x4_f32 v[228:231], v156, v180, v[228:231]
	v_pk_fma_f32 v[36:37], v[32:33], v[36:37], v[252:253]
	v_mfma_f32_16x16x4_f32 v[232:235], v156, v181, v[232:235]
	v_pk_fma_f32 v[252:253], v[34:35], v[36:37], v[202:203] op_sel:[0,1,0] op_sel_hi:[1,0,1] neg_lo:[1,0,0] neg_hi:[0,0,0]
	v_mfma_f32_16x16x4_f32 v[236:239], v156, v188, v[236:239]
	v_pk_fma_f32 v[36:37], v[32:33], v[36:37], v[252:253]
	v_mfma_f32_16x16x4_f32 v[240:243], v156, v189, v[240:243]
	ds_read_b128 v[192:195], v144 offset:49152
	s_waitcnt lgkmcnt(1)
	v_pk_fma_f32 v[252:253], v[34:35], v[36:37], v[244:245] op_sel:[0,1,0] op_sel_hi:[1,0,1] neg_lo:[1,0,0] neg_hi:[0,0,0]
	v_mfma_f32_16x16x4_f32 v[212:215], v157, v166, v[212:215]
	v_pk_fma_f32 v[36:37], v[32:33], v[36:37], v[252:253]
	v_mfma_f32_16x16x4_f32 v[216:219], v157, v167, v[216:219]
	v_pk_fma_f32 v[252:253], v[34:35], v[36:37], v[246:247] op_sel:[0,1,0] op_sel_hi:[1,0,1] neg_lo:[1,0,0] neg_hi:[0,0,0]
	v_mfma_f32_16x16x4_f32 v[220:223], v157, v174, v[220:223]
	v_pk_fma_f32 v[36:37], v[32:33], v[36:37], v[252:253]
	v_mfma_f32_16x16x4_f32 v[224:227], v157, v175, v[224:227]
	v_pk_fma_f32 v[252:253], v[34:35], v[36:37], v[248:249] op_sel:[0,1,0] op_sel_hi:[1,0,1] neg_lo:[1,0,0] neg_hi:[0,0,0]
	v_mfma_f32_16x16x4_f32 v[228:231], v157, v182, v[228:231]
	v_pk_fma_f32 v[36:37], v[32:33], v[36:37], v[252:253]
	v_mfma_f32_16x16x4_f32 v[232:235], v157, v183, v[232:235]
	v_pk_fma_f32 v[252:253], v[34:35], v[36:37], v[250:251] op_sel:[0,1,0] op_sel_hi:[1,0,1] neg_lo:[1,0,0] neg_hi:[0,0,0]
	v_mfma_f32_16x16x4_f32 v[236:239], v157, v190, v[236:239]
	v_pk_fma_f32 v[36:37], v[32:33], v[36:37], v[252:253]
	v_mfma_f32_16x16x4_f32 v[240:243], v157, v191, v[240:243]
	s_nop 9
	ds_write_b32 v145, v212
	ds_write_b32 v145, v213 offset:512
	ds_write_b32 v145, v214 offset:1024
	ds_write_b32 v145, v215 offset:1536
	ds_write_b32 v145, v216 offset:256
	ds_write_b32 v145, v217 offset:768
	ds_write_b32 v145, v218 offset:1280
	ds_write_b32 v145, v219 offset:1792
	ds_write_b32 v146, v220
	ds_write_b32 v146, v221 offset:512
	ds_write_b32 v146, v222 offset:1024
	ds_write_b32 v146, v223 offset:1536
	ds_write_b32 v146, v224 offset:256
	ds_write_b32 v146, v225 offset:768
	ds_write_b32 v146, v226 offset:1280
	ds_write_b32 v146, v227 offset:1792
	ds_write_b32 v147, v228
	ds_write_b32 v147, v229 offset:512
	ds_write_b32 v147, v230 offset:1024
	ds_write_b32 v147, v231 offset:1536
	ds_write_b32 v147, v232 offset:256
	ds_write_b32 v147, v233 offset:768
	ds_write_b32 v147, v234 offset:1280
	ds_write_b32 v147, v235 offset:1792
	ds_write_b32 v148, v236
	ds_write_b32 v148, v237 offset:512
	ds_write_b32 v148, v238 offset:1024
	ds_write_b32 v148, v239 offset:1536
	ds_write_b32 v148, v240 offset:256
	ds_write_b32 v148, v241 offset:768
	ds_write_b32 v148, v242 offset:1280
	ds_write_b32 v148, v243 offset:1792
	ds_read_b32 v196, v149
	ds_read_b32 v197, v149 offset:256
	ds_read_b32 v198, v149 offset:512
	ds_read_b32 v199, v149 offset:768
	ds_read_b32 v200, v149 offset:1024
	ds_read_b32 v201, v149 offset:1280
	ds_read_b32 v202, v149 offset:1536
	ds_read_b32 v203, v149 offset:1792
	ds_read_b32 v244, v150 offset:2048
	ds_read_b32 v245, v150 offset:2304
	ds_read_b32 v246, v150 offset:2560
	ds_read_b32 v247, v150 offset:2816
	ds_read_b32 v248, v150 offset:3072
	ds_read_b32 v249, v150 offset:3328
	ds_read_b32 v250, v150 offset:3584
	ds_read_b32 v251, v150 offset:3840
	s_waitcnt lgkmcnt(8)
	v_pk_fma_f32 v[252:253], v[34:35], v[36:37], v[196:197] op_sel:[0,1,0] op_sel_hi:[1,0,1] neg_lo:[1,0,0] neg_hi:[0,0,0]
	v_mfma_f32_16x16x4_f32 v[212:215], v192, v160, 0
	v_pk_fma_f32 v[36:37], v[32:33], v[36:37], v[252:253]
	v_mfma_f32_16x16x4_f32 v[216:219], v192, v161, 0
	v_pk_fma_f32 v[252:253], v[34:35], v[36:37], v[198:199] op_sel:[0,1,0] op_sel_hi:[1,0,1] neg_lo:[1,0,0] neg_hi:[0,0,0]
	v_mfma_f32_16x16x4_f32 v[220:223], v192, v168, 0
	v_pk_fma_f32 v[36:37], v[32:33], v[36:37], v[252:253]
	v_mfma_f32_16x16x4_f32 v[224:227], v192, v169, 0
	v_pk_fma_f32 v[252:253], v[34:35], v[36:37], v[200:201] op_sel:[0,1,0] op_sel_hi:[1,0,1] neg_lo:[1,0,0] neg_hi:[0,0,0]
	v_mfma_f32_16x16x4_f32 v[228:231], v192, v176, 0
	v_pk_fma_f32 v[36:37], v[32:33], v[36:37], v[252:253]
	v_mfma_f32_16x16x4_f32 v[232:235], v192, v177, 0
	v_pk_fma_f32 v[252:253], v[34:35], v[36:37], v[202:203] op_sel:[0,1,0] op_sel_hi:[1,0,1] neg_lo:[1,0,0] neg_hi:[0,0,0]
	v_mfma_f32_16x16x4_f32 v[236:239], v192, v184, 0
	v_pk_fma_f32 v[36:37], v[32:33], v[36:37], v[252:253]
	v_mfma_f32_16x16x4_f32 v[240:243], v192, v185, 0
	ds_read_b32 v196, v151 offset:4096
	ds_read_b32 v197, v151 offset:4352
	ds_read_b32 v198, v151 offset:4608
	ds_read_b32 v199, v151 offset:4864
	ds_read_b32 v200, v151 offset:5120
	ds_read_b32 v201, v151 offset:5376
	ds_read_b32 v202, v151 offset:5632
	ds_read_b32 v203, v151 offset:5888
	s_waitcnt lgkmcnt(8)
	v_pk_fma_f32 v[252:253], v[34:35], v[36:37], v[244:245] op_sel:[0,1,0] op_sel_hi:[1,0,1] neg_lo:[1,0,0] neg_hi:[0,0,0]
	v_mfma_f32_16x16x4_f32 v[212:215], v193, v162, v[212:215]
	v_pk_fma_f32 v[36:37], v[32:33], v[36:37], v[252:253]
	v_mfma_f32_16x16x4_f32 v[216:219], v193, v163, v[216:219]
	v_pk_fma_f32 v[252:253], v[34:35], v[36:37], v[246:247] op_sel:[0,1,0] op_sel_hi:[1,0,1] neg_lo:[1,0,0] neg_hi:[0,0,0]
	v_mfma_f32_16x16x4_f32 v[220:223], v193, v170, v[220:223]
	v_pk_fma_f32 v[36:37], v[32:33], v[36:37], v[252:253]
	v_mfma_f32_16x16x4_f32 v[224:227], v193, v171, v[224:227]
	v_pk_fma_f32 v[252:253], v[34:35], v[36:37], v[248:249] op_sel:[0,1,0] op_sel_hi:[1,0,1] neg_lo:[1,0,0] neg_hi:[0,0,0]
	v_mfma_f32_16x16x4_f32 v[228:231], v193, v178, v[228:231]
	v_pk_fma_f32 v[36:37], v[32:33], v[36:37], v[252:253]
	v_mfma_f32_16x16x4_f32 v[232:235], v193, v179, v[232:235]
	v_pk_fma_f32 v[252:253], v[34:35], v[36:37], v[250:251] op_sel:[0,1,0] op_sel_hi:[1,0,1] neg_lo:[1,0,0] neg_hi:[0,0,0]
	v_mfma_f32_16x16x4_f32 v[236:239], v193, v186, v[236:239]
	v_pk_fma_f32 v[36:37], v[32:33], v[36:37], v[252:253]
	v_mfma_f32_16x16x4_f32 v[240:243], v193, v187, v[240:243]
	ds_read_b32 v244, v152 offset:6144
	ds_read_b32 v245, v152 offset:6400
	ds_read_b32 v246, v152 offset:6656
	ds_read_b32 v247, v152 offset:6912
	ds_read_b32 v248, v152 offset:7168
	ds_read_b32 v249, v152 offset:7424
	ds_read_b32 v250, v152 offset:7680
	ds_read_b32 v251, v152 offset:7936
	s_waitcnt lgkmcnt(8)
	v_pk_fma_f32 v[252:253], v[34:35], v[36:37], v[196:197] op_sel:[0,1,0] op_sel_hi:[1,0,1] neg_lo:[1,0,0] neg_hi:[0,0,0]
	v_mfma_f32_16x16x4_f32 v[212:215], v194, v164, v[212:215]
	v_pk_fma_f32 v[36:37], v[32:33], v[36:37], v[252:253]
	v_mfma_f32_16x16x4_f32 v[216:219], v194, v165, v[216:219]
	v_pk_fma_f32 v[252:253], v[34:35], v[36:37], v[198:199] op_sel:[0,1,0] op_sel_hi:[1,0,1] neg_lo:[1,0,0] neg_hi:[0,0,0]
	v_mfma_f32_16x16x4_f32 v[220:223], v194, v172, v[220:223]
	v_pk_fma_f32 v[36:37], v[32:33], v[36:37], v[252:253]
	v_mfma_f32_16x16x4_f32 v[224:227], v194, v173, v[224:227]
	v_pk_fma_f32 v[252:253], v[34:35], v[36:37], v[200:201] op_sel:[0,1,0] op_sel_hi:[1,0,1] neg_lo:[1,0,0] neg_hi:[0,0,0]
	v_mfma_f32_16x16x4_f32 v[228:231], v194, v180, v[228:231]
	v_pk_fma_f32 v[36:37], v[32:33], v[36:37], v[252:253]
	v_mfma_f32_16x16x4_f32 v[232:235], v194, v181, v[232:235]
	v_pk_fma_f32 v[252:253], v[34:35], v[36:37], v[202:203] op_sel:[0,1,0] op_sel_hi:[1,0,1] neg_lo:[1,0,0] neg_hi:[0,0,0]
	v_mfma_f32_16x16x4_f32 v[236:239], v194, v188, v[236:239]
	v_pk_fma_f32 v[36:37], v[32:33], v[36:37], v[252:253]
	v_mfma_f32_16x16x4_f32 v[240:243], v194, v189, v[240:243]
	s_waitcnt lgkmcnt(0)
	v_pk_fma_f32 v[252:253], v[34:35], v[36:37], v[244:245] op_sel:[0,1,0] op_sel_hi:[1,0,1] neg_lo:[1,0,0] neg_hi:[0,0,0]
	v_mfma_f32_16x16x4_f32 v[212:215], v195, v166, v[212:215]
	v_pk_fma_f32 v[36:37], v[32:33], v[36:37], v[252:253]
	v_mfma_f32_16x16x4_f32 v[216:219], v195, v167, v[216:219]
	v_pk_fma_f32 v[252:253], v[34:35], v[36:37], v[246:247] op_sel:[0,1,0] op_sel_hi:[1,0,1] neg_lo:[1,0,0] neg_hi:[0,0,0]
	v_mfma_f32_16x16x4_f32 v[220:223], v195, v174, v[220:223]
	v_pk_fma_f32 v[36:37], v[32:33], v[36:37], v[252:253]
	v_mfma_f32_16x16x4_f32 v[224:227], v195, v175, v[224:227]
	v_pk_fma_f32 v[252:253], v[34:35], v[36:37], v[248:249] op_sel:[0,1,0] op_sel_hi:[1,0,1] neg_lo:[1,0,0] neg_hi:[0,0,0]
	v_mfma_f32_16x16x4_f32 v[228:231], v195, v182, v[228:231]
	v_pk_fma_f32 v[36:37], v[32:33], v[36:37], v[252:253]
	v_mfma_f32_16x16x4_f32 v[232:235], v195, v183, v[232:235]
	v_pk_fma_f32 v[252:253], v[34:35], v[36:37], v[250:251] op_sel:[0,1,0] op_sel_hi:[1,0,1] neg_lo:[1,0,0] neg_hi:[0,0,0]
	v_mfma_f32_16x16x4_f32 v[236:239], v195, v190, v[236:239]
	v_pk_fma_f32 v[36:37], v[32:33], v[36:37], v[252:253]
	v_mfma_f32_16x16x4_f32 v[240:243], v195, v191, v[240:243]
	s_nop 9
	ds_write_b32 v145, v212
	ds_write_b32 v145, v213 offset:512
	ds_write_b32 v145, v214 offset:1024
	ds_write_b32 v145, v215 offset:1536
	ds_write_b32 v145, v216 offset:256
	ds_write_b32 v145, v217 offset:768
	ds_write_b32 v145, v218 offset:1280
	ds_write_b32 v145, v219 offset:1792
	ds_write_b32 v146, v220
	ds_write_b32 v146, v221 offset:512
	ds_write_b32 v146, v222 offset:1024
	ds_write_b32 v146, v223 offset:1536
	ds_write_b32 v146, v224 offset:256
	ds_write_b32 v146, v225 offset:768
	ds_write_b32 v146, v226 offset:1280
	ds_write_b32 v146, v227 offset:1792
	ds_write_b32 v147, v228
	ds_write_b32 v147, v229 offset:512
	ds_write_b32 v147, v230 offset:1024
	ds_write_b32 v147, v231 offset:1536
	ds_write_b32 v147, v232 offset:256
	ds_write_b32 v147, v233 offset:768
	ds_write_b32 v147, v234 offset:1280
	ds_write_b32 v147, v235 offset:1792
	ds_write_b32 v148, v236
	ds_write_b32 v148, v237 offset:512
	ds_write_b32 v148, v238 offset:1024
	ds_write_b32 v148, v239 offset:1536
	ds_write_b32 v148, v240 offset:256
	ds_write_b32 v148, v241 offset:768
	ds_write_b32 v148, v242 offset:1280
	ds_write_b32 v148, v243 offset:1792
	ds_read_b32 v196, v149
	ds_read_b32 v197, v149 offset:256
	ds_read_b32 v198, v149 offset:512
	ds_read_b32 v199, v149 offset:768
	ds_read_b32 v200, v149 offset:1024
	ds_read_b32 v201, v149 offset:1280
	ds_read_b32 v202, v149 offset:1536
	ds_read_b32 v203, v149 offset:1792
	ds_read_b32 v244, v150 offset:2048
	ds_read_b32 v245, v150 offset:2304
	ds_read_b32 v246, v150 offset:2560
	ds_read_b32 v247, v150 offset:2816
	ds_read_b32 v248, v150 offset:3072
	ds_read_b32 v249, v150 offset:3328
	ds_read_b32 v250, v150 offset:3584
	ds_read_b32 v251, v150 offset:3840
	s_waitcnt lgkmcnt(8)
	v_pk_fma_f32 v[252:253], v[34:35], v[36:37], v[196:197] op_sel:[0,1,0] op_sel_hi:[1,0,1] neg_lo:[1,0,0] neg_hi:[0,0,0]
	s_nop 0
	v_pk_fma_f32 v[36:37], v[32:33], v[36:37], v[252:253]
	s_nop 0
	v_pk_fma_f32 v[252:253], v[34:35], v[36:37], v[198:199] op_sel:[0,1,0] op_sel_hi:[1,0,1] neg_lo:[1,0,0] neg_hi:[0,0,0]
	s_nop 0
	v_pk_fma_f32 v[36:37], v[32:33], v[36:37], v[252:253]
	s_nop 0
	v_pk_fma_f32 v[252:253], v[34:35], v[36:37], v[200:201] op_sel:[0,1,0] op_sel_hi:[1,0,1] neg_lo:[1,0,0] neg_hi:[0,0,0]
	s_nop 0
	v_pk_fma_f32 v[36:37], v[32:33], v[36:37], v[252:253]
	s_nop 0
	v_pk_fma_f32 v[252:253], v[34:35], v[36:37], v[202:203] op_sel:[0,1,0] op_sel_hi:[1,0,1] neg_lo:[1,0,0] neg_hi:[0,0,0]
	s_nop 0
	v_pk_fma_f32 v[36:37], v[32:33], v[36:37], v[252:253]
	s_nop 0
	ds_read_b32 v196, v151 offset:4096
	ds_read_b32 v197, v151 offset:4352
	ds_read_b32 v198, v151 offset:4608
	ds_read_b32 v199, v151 offset:4864
	ds_read_b32 v200, v151 offset:5120
	ds_read_b32 v201, v151 offset:5376
	ds_read_b32 v202, v151 offset:5632
	ds_read_b32 v203, v151 offset:5888
	s_waitcnt lgkmcnt(8)
	v_pk_fma_f32 v[252:253], v[34:35], v[36:37], v[244:245] op_sel:[0,1,0] op_sel_hi:[1,0,1] neg_lo:[1,0,0] neg_hi:[0,0,0]
	s_nop 0
	v_pk_fma_f32 v[36:37], v[32:33], v[36:37], v[252:253]
	s_nop 0
	v_pk_fma_f32 v[252:253], v[34:35], v[36:37], v[246:247] op_sel:[0,1,0] op_sel_hi:[1,0,1] neg_lo:[1,0,0] neg_hi:[0,0,0]
	s_nop 0
	v_pk_fma_f32 v[36:37], v[32:33], v[36:37], v[252:253]
	s_nop 0
	v_pk_fma_f32 v[252:253], v[34:35], v[36:37], v[248:249] op_sel:[0,1,0] op_sel_hi:[1,0,1] neg_lo:[1,0,0] neg_hi:[0,0,0]
	s_nop 0
	v_pk_fma_f32 v[36:37], v[32:33], v[36:37], v[252:253]
	s_nop 0
	v_pk_fma_f32 v[252:253], v[34:35], v[36:37], v[250:251] op_sel:[0,1,0] op_sel_hi:[1,0,1] neg_lo:[1,0,0] neg_hi:[0,0,0]
	s_nop 0
	v_pk_fma_f32 v[36:37], v[32:33], v[36:37], v[252:253]
	s_nop 0
	ds_read_b32 v244, v152 offset:6144
	ds_read_b32 v245, v152 offset:6400
	ds_read_b32 v246, v152 offset:6656
	ds_read_b32 v247, v152 offset:6912
	ds_read_b32 v248, v152 offset:7168
	ds_read_b32 v249, v152 offset:7424
	ds_read_b32 v250, v152 offset:7680
	ds_read_b32 v251, v152 offset:7936
	s_waitcnt lgkmcnt(8)
	v_pk_fma_f32 v[252:253], v[34:35], v[36:37], v[196:197] op_sel:[0,1,0] op_sel_hi:[1,0,1] neg_lo:[1,0,0] neg_hi:[0,0,0]
	s_nop 0
	v_pk_fma_f32 v[36:37], v[32:33], v[36:37], v[252:253]
	s_nop 0
	v_pk_fma_f32 v[252:253], v[34:35], v[36:37], v[198:199] op_sel:[0,1,0] op_sel_hi:[1,0,1] neg_lo:[1,0,0] neg_hi:[0,0,0]
	s_nop 0
	v_pk_fma_f32 v[36:37], v[32:33], v[36:37], v[252:253]
	s_nop 0
	v_pk_fma_f32 v[252:253], v[34:35], v[36:37], v[200:201] op_sel:[0,1,0] op_sel_hi:[1,0,1] neg_lo:[1,0,0] neg_hi:[0,0,0]
	s_nop 0
	v_pk_fma_f32 v[36:37], v[32:33], v[36:37], v[252:253]
	s_nop 0
	v_pk_fma_f32 v[252:253], v[34:35], v[36:37], v[202:203] op_sel:[0,1,0] op_sel_hi:[1,0,1] neg_lo:[1,0,0] neg_hi:[0,0,0]
	s_nop 0
	v_pk_fma_f32 v[36:37], v[32:33], v[36:37], v[252:253]
	s_nop 0
	s_waitcnt lgkmcnt(0)
	v_pk_fma_f32 v[252:253], v[34:35], v[36:37], v[244:245] op_sel:[0,1,0] op_sel_hi:[1,0,1] neg_lo:[1,0,0] neg_hi:[0,0,0]
	s_nop 0
	v_pk_fma_f32 v[36:37], v[32:33], v[36:37], v[252:253]
	s_nop 0
	v_pk_fma_f32 v[252:253], v[34:35], v[36:37], v[246:247] op_sel:[0,1,0] op_sel_hi:[1,0,1] neg_lo:[1,0,0] neg_hi:[0,0,0]
	s_nop 0
	v_pk_fma_f32 v[36:37], v[32:33], v[36:37], v[252:253]
	s_nop 0
	v_pk_fma_f32 v[252:253], v[34:35], v[36:37], v[248:249] op_sel:[0,1,0] op_sel_hi:[1,0,1] neg_lo:[1,0,0] neg_hi:[0,0,0]
	s_nop 0
	v_pk_fma_f32 v[36:37], v[32:33], v[36:37], v[252:253]
	s_nop 0
	v_pk_fma_f32 v[252:253], v[34:35], v[36:37], v[250:251] op_sel:[0,1,0] op_sel_hi:[1,0,1] neg_lo:[1,0,0] neg_hi:[0,0,0]
	s_nop 0
	v_pk_fma_f32 v[36:37], v[32:33], v[36:37], v[252:253]
	s_nop 0
	s_lshl_b64 s[10:11], s[38:39], 9
	v_lshl_add_u64 v[30:31], v[28:29], 0, s[10:11]
	s_mov_b32 s10, 8
	s_mov_b64 s[44:45], 0
	s_and_b64 vcc, exec, s[12:13]
	global_store_dwordx2 v[30:31], v[36:37], off
	s_cbranch_vccz .LBB0_496
	v_add_u32_e32 v28, s18, v68
	v_ashrrev_i32_e32 v29, 31, v28
	v_lshlrev_b64 v[30:31], 10, v[28:29]
	v_lshl_add_u64 v[30:31], v[8:9], 0, v[30:31]
	s_barrier
	global_load_ushort v108, v[30:31], off
	v_and_b32_e32 v27, 0x1fe0, v28
	v_cmp_ne_u32_e32 vcc, 0, v27
	v_mov_b32_e32 v110, 0
	s_and_saveexec_b64 s[10:11], vcc
	s_cbranch_execz .LBB0_509
	global_load_ushort v1, v[30:31], off offset:-512
	s_waitcnt vmcnt(0)
	v_cvt_f32_f16_e32 v110, v1

.LBB0_2214:
	v_mbcnt_lo_u32_b32 v140, -1, 0
	v_mbcnt_hi_u32_b32 v140, -1, v140
	s_and_b32 s11, s44, 7
	s_lshl_b32 s11, s11, 13
	s_add_i32 s11, s11, 0x10000
	v_and_b32_e32 v196, 15, v140
	v_lshrrev_b32_e32 v197, 4, v140
	v_bfe_u32 v198, v140, 1, 3
	v_lshlrev_b32_e32 v141, 7, v140
	v_lshl_or_b32 v141, v198, 4, v141
	v_add_u32_e32 v141, s11, v141
	v_xor_b32_e32 v245, 16, v141
	v_xor_b32_e32 v246, 32, v141
	v_xor_b32_e32 v247, 48, v141
	v_xor_b32_e32 v248, 64, v141
	v_xor_b32_e32 v249, 80, v141
	v_xor_b32_e32 v250, 96, v141
	v_xor_b32_e32 v251, 112, v141
	ds_write_b64 v141, v[32:33]
	ds_write_b64 v141, v[40:41] offset:8
	ds_write_b64 v245, v[42:43]
	ds_write_b64 v245, v[44:45] offset:8
	ds_write_b64 v246, v[46:47]
	ds_write_b64 v246, v[48:49] offset:8
	ds_write_b64 v247, v[50:51]
	ds_write_b64 v247, v[52:53] offset:8
	ds_write_b64 v248, v[54:55]
	ds_write_b64 v248, v[56:57] offset:8
	ds_write_b64 v249, v[58:59]
	ds_write_b64 v249, v[60:61] offset:8
	ds_write_b64 v250, v[62:63]
	ds_write_b64 v250, v[64:65] offset:8
	ds_write_b64 v251, v[66:67]
	ds_write_b64 v251, v[68:69] offset:8
	v_bfe_u32 v198, v196, 1, 3
	v_lshlrev_b32_e32 v199, 1, v197
	v_xor_b32_e32 v199, v199, v198
	v_lshlrev_b32_e32 v142, 7, v196
	v_lshl_or_b32 v142, v199, 4, v142
	v_add_u32_e32 v142, s11, v142
	v_xor_b32_e32 v143, 16, v142
	ds_read_b128 v[160:163], v142
	ds_read_b128 v[164:167], v143
	ds_read_b128 v[168:171], v142 offset:2048
	ds_read_b128 v[172:175], v143 offset:2048
	ds_read_b128 v[176:179], v142 offset:4096
	ds_read_b128 v[180:183], v143 offset:4096
	ds_read_b128 v[184:187], v142 offset:6144
	ds_read_b128 v[188:191], v143 offset:6144
	v_lshlrev_b32_e32 v144, 10, v196
	v_lshl_add_u32 v144, v197, 4, v144
	v_add_u32_e32 v144, s10, v144
	ds_read_b128 v[154:157], v144
	ds_read_b128 v[192:195], v144 offset:16384
	v_lshlrev_b32_e32 v198, 11, v197
	v_lshl_add_u32 v198, v196, 2, v198
	v_add_u32_e32 v198, s11, v198
	v_mov_b32_e32 v199, v197
	v_lshl_add_u32 v145, v199, 6, v198
	v_xor_b32_e32 v199, 1, v197
	v_lshl_add_u32 v146, v199, 6, v198
	v_xor_b32_e32 v199, 2, v197
	v_lshl_add_u32 v147, v199, 6, v198
	v_xor_b32_e32 v199, 3, v197
	v_lshl_add_u32 v148, v199, 6, v198
	v_lshlrev_b32_e32 v198, 2, v140
	v_add_u32_e32 v149, s11, v198
	v_xor_b32_e32 v199, 64, v198
	v_add_u32_e32 v150, s11, v199
	v_xor_b32_e32 v199, 128, v198
	v_add_u32_e32 v151, s11, v199
	v_xor_b32_e32 v199, 192, v198
	v_add_u32_e32 v152, s11, v199
	s_waitcnt lgkmcnt(0)
	v_mfma_f32_16x16x4_f32 v[212:215], v154, v160, 0
	v_mfma_f32_16x16x4_f32 v[216:219], v154, v161, 0
	v_mfma_f32_16x16x4_f32 v[220:223], v154, v168, 0
	v_mfma_f32_16x16x4_f32 v[224:227], v154, v169, 0
	v_mfma_f32_16x16x4_f32 v[228:231], v154, v176, 0
	v_mfma_f32_16x16x4_f32 v[232:235], v154, v177, 0
	v_mfma_f32_16x16x4_f32 v[236:239], v154, v184, 0
	v_mfma_f32_16x16x4_f32 v[240:243], v154, v185, 0
	v_mfma_f32_16x16x4_f32 v[212:215], v155, v162, v[212:215]
	v_mfma_f32_16x16x4_f32 v[216:219], v155, v163, v[216:219]
	v_mfma_f32_16x16x4_f32 v[220:223], v155, v170, v[220:223]
	v_mfma_f32_16x16x4_f32 v[224:227], v155, v171, v[224:227]
	v_mfma_f32_16x16x4_f32 v[228:231], v155, v178, v[228:231]
	v_mfma_f32_16x16x4_f32 v[232:235], v155, v179, v[232:235]
	v_mfma_f32_16x16x4_f32 v[236:239], v155, v186, v[236:239]
	v_mfma_f32_16x16x4_f32 v[240:243], v155, v187, v[240:243]
	v_mfma_f32_16x16x4_f32 v[212:215], v156, v164, v[212:215]
	v_mfma_f32_16x16x4_f32 v[216:219], v156, v165, v[216:219]
	v_mfma_f32_16x16x4_f32 v[220:223], v156, v172, v[220:223]
	v_mfma_f32_16x16x4_f32 v[224:227], v156, v173, v[224:227]
	v_mfma_f32_16x16x4_f32 v[228:231], v156, v180, v[228:231]
	v_mfma_f32_16x16x4_f32 v[232:235], v156, v181, v[232:235]
	v_mfma_f32_16x16x4_f32 v[236:239], v156, v188, v[236:239]
	v_mfma_f32_16x16x4_f32 v[240:243], v156, v189, v[240:243]
	v_mfma_f32_16x16x4_f32 v[212:215], v157, v166, v[212:215]
	v_mfma_f32_16x16x4_f32 v[216:219], v157, v167, v[216:219]
	v_mfma_f32_16x16x4_f32 v[220:223], v157, v174, v[220:223]
	v_mfma_f32_16x16x4_f32 v[224:227], v157, v175, v[224:227]
	v_mfma_f32_16x16x4_f32 v[228:231], v157, v182, v[228:231]
	v_mfma_f32_16x16x4_f32 v[232:235], v157, v183, v[232:235]
	v_mfma_f32_16x16x4_f32 v[236:239], v157, v190, v[236:239]
	v_mfma_f32_16x16x4_f32 v[240:243], v157, v191, v[240:243]
	s_nop 9
	ds_write_b32 v145, v212
	ds_write_b32 v145, v213 offset:512
	ds_write_b32 v145, v214 offset:1024
	ds_write_b32 v145, v215 offset:1536
	ds_write_b32 v145, v216 offset:256
	ds_write_b32 v145, v217 offset:768
	ds_write_b32 v145, v218 offset:1280
	ds_write_b32 v145, v219 offset:1792
	ds_write_b32 v146, v220
	ds_write_b32 v146, v221 offset:512
	ds_write_b32 v146, v222 offset:1024
	ds_write_b32 v146, v223 offset:1536
	ds_write_b32 v146, v224 offset:256
	ds_write_b32 v146, v225 offset:768
	ds_write_b32 v146, v226 offset:1280
	ds_write_b32 v146, v227 offset:1792
	ds_write_b32 v147, v228
	ds_write_b32 v147, v229 offset:512
	ds_write_b32 v147, v230 offset:1024
	ds_write_b32 v147, v231 offset:1536
	ds_write_b32 v147, v232 offset:256
	ds_write_b32 v147, v233 offset:768
	ds_write_b32 v147, v234 offset:1280
	ds_write_b32 v147, v235 offset:1792
	ds_write_b32 v148, v236
	ds_write_b32 v148, v237 offset:512
	ds_write_b32 v148, v238 offset:1024
	ds_write_b32 v148, v239 offset:1536
	ds_write_b32 v148, v240 offset:256
	ds_write_b32 v148, v241 offset:768
	ds_write_b32 v148, v242 offset:1280
	ds_write_b32 v148, v243 offset:1792
	ds_read_b32 v196, v149
	ds_read_b32 v197, v149 offset:256
	ds_read_b32 v198, v149 offset:512
	ds_read_b32 v199, v149 offset:768
	ds_read_b32 v200, v149 offset:1024
	ds_read_b32 v201, v149 offset:1280
	ds_read_b32 v202, v149 offset:1536
	ds_read_b32 v203, v149 offset:1792
	ds_read_b32 v244, v150 offset:2048
	ds_read_b32 v245, v150 offset:2304
	ds_read_b32 v246, v150 offset:2560
	ds_read_b32 v247, v150 offset:2816
	ds_read_b32 v248, v150 offset:3072
	ds_read_b32 v249, v150 offset:3328
	ds_read_b32 v250, v150 offset:3584
	ds_read_b32 v251, v150 offset:3840
	s_waitcnt lgkmcnt(8)
	v_pk_fma_f32 v[252:253], v[36:37], v[38:39], v[196:197] op_sel:[0,1,0] op_sel_hi:[1,0,1] neg_lo:[1,0,0] neg_hi:[0,0,0]
	v_mfma_f32_16x16x4_f32 v[212:215], v192, v160, 0
	v_pk_fma_f32 v[38:39], v[34:35], v[38:39], v[252:253]
	v_mfma_f32_16x16x4_f32 v[216:219], v192, v161, 0
	v_pk_fma_f32 v[252:253], v[36:37], v[38:39], v[198:199] op_sel:[0,1,0] op_sel_hi:[1,0,1] neg_lo:[1,0,0] neg_hi:[0,0,0]
	v_mfma_f32_16x16x4_f32 v[220:223], v192, v168, 0
	v_pk_fma_f32 v[38:39], v[34:35], v[38:39], v[252:253]
	v_mfma_f32_16x16x4_f32 v[224:227], v192, v169, 0
	v_pk_fma_f32 v[252:253], v[36:37], v[38:39], v[200:201] op_sel:[0,1,0] op_sel_hi:[1,0,1] neg_lo:[1,0,0] neg_hi:[0,0,0]
	v_mfma_f32_16x16x4_f32 v[228:231], v192, v176, 0
	v_pk_fma_f32 v[38:39], v[34:35], v[38:39], v[252:253]
	v_mfma_f32_16x16x4_f32 v[232:235], v192, v177, 0
	v_pk_fma_f32 v[252:253], v[36:37], v[38:39], v[202:203] op_sel:[0,1,0] op_sel_hi:[1,0,1] neg_lo:[1,0,0] neg_hi:[0,0,0]
	v_mfma_f32_16x16x4_f32 v[236:239], v192, v184, 0
	v_pk_fma_f32 v[38:39], v[34:35], v[38:39], v[252:253]
	v_mfma_f32_16x16x4_f32 v[240:243], v192, v185, 0
	ds_read_b32 v196, v151 offset:4096
	ds_read_b32 v197, v151 offset:4352
	ds_read_b32 v198, v151 offset:4608
	ds_read_b32 v199, v151 offset:4864
	ds_read_b32 v200, v151 offset:5120
	ds_read_b32 v201, v151 offset:5376
	ds_read_b32 v202, v151 offset:5632
	ds_read_b32 v203, v151 offset:5888
	s_waitcnt lgkmcnt(8)
	v_pk_fma_f32 v[252:253], v[36:37], v[38:39], v[244:245] op_sel:[0,1,0] op_sel_hi:[1,0,1] neg_lo:[1,0,0] neg_hi:[0,0,0]
	v_mfma_f32_16x16x4_f32 v[212:215], v193, v162, v[212:215]
	v_pk_fma_f32 v[38:39], v[34:35], v[38:39], v[252:253]
	v_mfma_f32_16x16x4_f32 v[216:219], v193, v163, v[216:219]
	v_pk_fma_f32 v[252:253], v[36:37], v[38:39], v[246:247] op_sel:[0,1,0] op_sel_hi:[1,0,1] neg_lo:[1,0,0] neg_hi:[0,0,0]
	v_mfma_f32_16x16x4_f32 v[220:223], v193, v170, v[220:223]
	v_pk_fma_f32 v[38:39], v[34:35], v[38:39], v[252:253]
	v_mfma_f32_16x16x4_f32 v[224:227], v193, v171, v[224:227]
	v_pk_fma_f32 v[252:253], v[36:37], v[38:39], v[248:249] op_sel:[0,1,0] op_sel_hi:[1,0,1] neg_lo:[1,0,0] neg_hi:[0,0,0]
	v_mfma_f32_16x16x4_f32 v[228:231], v193, v178, v[228:231]
	v_pk_fma_f32 v[38:39], v[34:35], v[38:39], v[252:253]
	v_mfma_f32_16x16x4_f32 v[232:235], v193, v179, v[232:235]
	v_pk_fma_f32 v[252:253], v[36:37], v[38:39], v[250:251] op_sel:[0,1,0] op_sel_hi:[1,0,1] neg_lo:[1,0,0] neg_hi:[0,0,0]
	v_mfma_f32_16x16x4_f32 v[236:239], v193, v186, v[236:239]
	v_pk_fma_f32 v[38:39], v[34:35], v[38:39], v[252:253]
	v_mfma_f32_16x16x4_f32 v[240:243], v193, v187, v[240:243]
	ds_read_b32 v244, v152 offset:6144
	ds_read_b32 v245, v152 offset:6400
	ds_read_b32 v246, v152 offset:6656
	ds_read_b32 v247, v152 offset:6912
	ds_read_b32 v248, v152 offset:7168
	ds_read_b32 v249, v152 offset:7424
	ds_read_b32 v250, v152 offset:7680
	ds_read_b32 v251, v152 offset:7936
	s_waitcnt lgkmcnt(8)
	v_pk_fma_f32 v[252:253], v[36:37], v[38:39], v[196:197] op_sel:[0,1,0] op_sel_hi:[1,0,1] neg_lo:[1,0,0] neg_hi:[0,0,0]
	v_mfma_f32_16x16x4_f32 v[212:215], v194, v164, v[212:215]
	v_pk_fma_f32 v[38:39], v[34:35], v[38:39], v[252:253]
	v_mfma_f32_16x16x4_f32 v[216:219], v194, v165, v[216:219]
	v_pk_fma_f32 v[252:253], v[36:37], v[38:39], v[198:199] op_sel:[0,1,0] op_sel_hi:[1,0,1] neg_lo:[1,0,0] neg_hi:[0,0,0]
	v_mfma_f32_16x16x4_f32 v[220:223], v194, v172, v[220:223]
	v_pk_fma_f32 v[38:39], v[34:35], v[38:39], v[252:253]
	v_mfma_f32_16x16x4_f32 v[224:227], v194, v173, v[224:227]
	v_pk_fma_f32 v[252:253], v[36:37], v[38:39], v[200:201] op_sel:[0,1,0] op_sel_hi:[1,0,1] neg_lo:[1,0,0] neg_hi:[0,0,0]
	v_mfma_f32_16x16x4_f32 v[228:231], v194, v180, v[228:231]
	v_pk_fma_f32 v[38:39], v[34:35], v[38:39], v[252:253]
	v_mfma_f32_16x16x4_f32 v[232:235], v194, v181, v[232:235]
	v_pk_fma_f32 v[252:253], v[36:37], v[38:39], v[202:203] op_sel:[0,1,0] op_sel_hi:[1,0,1] neg_lo:[1,0,0] neg_hi:[0,0,0]
	v_mfma_f32_16x16x4_f32 v[236:239], v194, v188, v[236:239]
	v_pk_fma_f32 v[38:39], v[34:35], v[38:39], v[252:253]
	v_mfma_f32_16x16x4_f32 v[240:243], v194, v189, v[240:243]
	ds_read_b128 v[154:157], v144 offset:32768
	s_waitcnt lgkmcnt(1)
	v_pk_fma_f32 v[252:253], v[36:37], v[38:39], v[244:245] op_sel:[0,1,0] op_sel_hi:[1,0,1] neg_lo:[1,0,0] neg_hi:[0,0,0]
	v_mfma_f32_16x16x4_f32 v[212:215], v195, v166, v[212:215]
	v_pk_fma_f32 v[38:39], v[34:35], v[38:39], v[252:253]
	v_mfma_f32_16x16x4_f32 v[216:219], v195, v167, v[216:219]
	v_pk_fma_f32 v[252:253], v[36:37], v[38:39], v[246:247] op_sel:[0,1,0] op_sel_hi:[1,0,1] neg_lo:[1,0,0] neg_hi:[0,0,0]
	v_mfma_f32_16x16x4_f32 v[220:223], v195, v174, v[220:223]
	v_pk_fma_f32 v[38:39], v[34:35], v[38:39], v[252:253]
	v_mfma_f32_16x16x4_f32 v[224:227], v195, v175, v[224:227]
	v_pk_fma_f32 v[252:253], v[36:37], v[38:39], v[248:249] op_sel:[0,1,0] op_sel_hi:[1,0,1] neg_lo:[1,0,0] neg_hi:[0,0,0]
	v_mfma_f32_16x16x4_f32 v[228:231], v195, v182, v[228:231]
	v_pk_fma_f32 v[38:39], v[34:35], v[38:39], v[252:253]
	v_mfma_f32_16x16x4_f32 v[232:235], v195, v183, v[232:235]
	v_pk_fma_f32 v[252:253], v[36:37], v[38:39], v[250:251] op_sel:[0,1,0] op_sel_hi:[1,0,1] neg_lo:[1,0,0] neg_hi:[0,0,0]
	v_mfma_f32_16x16x4_f32 v[236:239], v195, v190, v[236:239]
	v_pk_fma_f32 v[38:39], v[34:35], v[38:39], v[252:253]
	v_mfma_f32_16x16x4_f32 v[240:243], v195, v191, v[240:243]
	s_nop 9
	ds_write_b32 v145, v212
	ds_write_b32 v145, v213 offset:512
	ds_write_b32 v145, v214 offset:1024
	ds_write_b32 v145, v215 offset:1536
	ds_write_b32 v145, v216 offset:256
	ds_write_b32 v145, v217 offset:768
	ds_write_b32 v145, v218 offset:1280
	ds_write_b32 v145, v219 offset:1792
	ds_write_b32 v146, v220
	ds_write_b32 v146, v221 offset:512
	ds_write_b32 v146, v222 offset:1024
	ds_write_b32 v146, v223 offset:1536
	ds_write_b32 v146, v224 offset:256
	ds_write_b32 v146, v225 offset:768
	ds_write_b32 v146, v226 offset:1280
	ds_write_b32 v146, v227 offset:1792
	ds_write_b32 v147, v228
	ds_write_b32 v147, v229 offset:512
	ds_write_b32 v147, v230 offset:1024
	ds_write_b32 v147, v231 offset:1536
	ds_write_b32 v147, v232 offset:256
	ds_write_b32 v147, v233 offset:768
	ds_write_b32 v147, v234 offset:1280
	ds_write_b32 v147, v235 offset:1792
	ds_write_b32 v148, v236
	ds_write_b32 v148, v237 offset:512
	ds_write_b32 v148, v238 offset:1024
	ds_write_b32 v148, v239 offset:1536
	ds_write_b32 v148, v240 offset:256
	ds_write_b32 v148, v241 offset:768
	ds_write_b32 v148, v242 offset:1280
	ds_write_b32 v148, v243 offset:1792
	ds_read_b32 v196, v149
	ds_read_b32 v197, v149 offset:256
	ds_read_b32 v198, v149 offset:512
	ds_read_b32 v199, v149 offset:768
	ds_read_b32 v200, v149 offset:1024
	ds_read_b32 v201, v149 offset:1280
	ds_read_b32 v202, v149 offset:1536
	ds_read_b32 v203, v149 offset:1792
	ds_read_b32 v244, v150 offset:2048
	ds_read_b32 v245, v150 offset:2304
	ds_read_b32 v246, v150 offset:2560
	ds_read_b32 v247, v150 offset:2816
	ds_read_b32 v248, v150 offset:3072
	ds_read_b32 v249, v150 offset:3328
	ds_read_b32 v250, v150 offset:3584
	ds_read_b32 v251, v150 offset:3840
	s_waitcnt lgkmcnt(8)
	v_pk_fma_f32 v[252:253], v[36:37], v[38:39], v[196:197] op_sel:[0,1,0] op_sel_hi:[1,0,1] neg_lo:[1,0,0] neg_hi:[0,0,0]
	v_mfma_f32_16x16x4_f32 v[212:215], v154, v160, 0
	v_pk_fma_f32 v[38:39], v[34:35], v[38:39], v[252:253]
	v_mfma_f32_16x16x4_f32 v[216:219], v154, v161, 0
	v_pk_fma_f32 v[252:253], v[36:37], v[38:39], v[198:199] op_sel:[0,1,0] op_sel_hi:[1,0,1] neg_lo:[1,0,0] neg_hi:[0,0,0]
	v_mfma_f32_16x16x4_f32 v[220:223], v154, v168, 0
	v_pk_fma_f32 v[38:39], v[34:35], v[38:39], v[252:253]
	v_mfma_f32_16x16x4_f32 v[224:227], v154, v169, 0
	v_pk_fma_f32 v[252:253], v[36:37], v[38:39], v[200:201] op_sel:[0,1,0] op_sel_hi:[1,0,1] neg_lo:[1,0,0] neg_hi:[0,0,0]
	v_mfma_f32_16x16x4_f32 v[228:231], v154, v176, 0
	v_pk_fma_f32 v[38:39], v[34:35], v[38:39], v[252:253]
	v_mfma_f32_16x16x4_f32 v[232:235], v154, v177, 0
	v_pk_fma_f32 v[252:253], v[36:37], v[38:39], v[202:203] op_sel:[0,1,0] op_sel_hi:[1,0,1] neg_lo:[1,0,0] neg_hi:[0,0,0]
	v_mfma_f32_16x16x4_f32 v[236:239], v154, v184, 0
	v_pk_fma_f32 v[38:39], v[34:35], v[38:39], v[252:253]
	v_mfma_f32_16x16x4_f32 v[240:243], v154, v185, 0
	ds_read_b32 v196, v151 offset:4096
	ds_read_b32 v197, v151 offset:4352
	ds_read_b32 v198, v151 offset:4608
	ds_read_b32 v199, v151 offset:4864
	ds_read_b32 v200, v151 offset:5120
	ds_read_b32 v201, v151 offset:5376
	ds_read_b32 v202, v151 offset:5632
	ds_read_b32 v203, v151 offset:5888
	s_waitcnt lgkmcnt(8)
	v_pk_fma_f32 v[252:253], v[36:37], v[38:39], v[244:245] op_sel:[0,1,0] op_sel_hi:[1,0,1] neg_lo:[1,0,0] neg_hi:[0,0,0]
	v_mfma_f32_16x16x4_f32 v[212:215], v155, v162, v[212:215]
	v_pk_fma_f32 v[38:39], v[34:35], v[38:39], v[252:253]
	v_mfma_f32_16x16x4_f32 v[216:219], v155, v163, v[216:219]
	v_pk_fma_f32 v[252:253], v[36:37], v[38:39], v[246:247] op_sel:[0,1,0] op_sel_hi:[1,0,1] neg_lo:[1,0,0] neg_hi:[0,0,0]
	v_mfma_f32_16x16x4_f32 v[220:223], v155, v170, v[220:223]
	v_pk_fma_f32 v[38:39], v[34:35], v[38:39], v[252:253]
	v_mfma_f32_16x16x4_f32 v[224:227], v155, v171, v[224:227]
	v_pk_fma_f32 v[252:253], v[36:37], v[38:39], v[248:249] op_sel:[0,1,0] op_sel_hi:[1,0,1] neg_lo:[1,0,0] neg_hi:[0,0,0]
	v_mfma_f32_16x16x4_f32 v[228:231], v155, v178, v[228:231]
	v_pk_fma_f32 v[38:39], v[34:35], v[38:39], v[252:253]
	v_mfma_f32_16x16x4_f32 v[232:235], v155, v179, v[232:235]
	v_pk_fma_f32 v[252:253], v[36:37], v[38:39], v[250:251] op_sel:[0,1,0] op_sel_hi:[1,0,1] neg_lo:[1,0,0] neg_hi:[0,0,0]
	v_mfma_f32_16x16x4_f32 v[236:239], v155, v186, v[236:239]
	v_pk_fma_f32 v[38:39], v[34:35], v[38:39], v[252:253]
	v_mfma_f32_16x16x4_f32 v[240:243], v155, v187, v[240:243]
	ds_read_b32 v244, v152 offset:6144
	ds_read_b32 v245, v152 offset:6400
	ds_read_b32 v246, v152 offset:6656
	ds_read_b32 v247, v152 offset:6912
	ds_read_b32 v248, v152 offset:7168
	ds_read_b32 v249, v152 offset:7424
	ds_read_b32 v250, v152 offset:7680
	ds_read_b32 v251, v152 offset:7936
	s_waitcnt lgkmcnt(8)
	v_pk_fma_f32 v[252:253], v[36:37], v[38:39], v[196:197] op_sel:[0,1,0] op_sel_hi:[1,0,1] neg_lo:[1,0,0] neg_hi:[0,0,0]
	v_mfma_f32_16x16x4_f32 v[212:215], v156, v164, v[212:215]
	v_pk_fma_f32 v[38:39], v[34:35], v[38:39], v[252:253]
	v_mfma_f32_16x16x4_f32 v[216:219], v156, v165, v[216:219]
	v_pk_fma_f32 v[252:253], v[36:37], v[38:39], v[198:199] op_sel:[0,1,0] op_sel_hi:[1,0,1] neg_lo:[1,0,0] neg_hi:[0,0,0]
	v_mfma_f32_16x16x4_f32 v[220:223], v156, v172, v[220:223]
	v_pk_fma_f32 v[38:39], v[34:35], v[38:39], v[252:253]
	v_mfma_f32_16x16x4_f32 v[224:227], v156, v173, v[224:227]
	v_pk_fma_f32 v[252:253], v[36:37], v[38:39], v[200:201] op_sel:[0,1,0] op_sel_hi:[1,0,1] neg_lo:[1,0,0] neg_hi:[0,0,0]
	v_mfma_f32_16x16x4_f32 v[228:231], v156, v180, v[228:231]
	v_pk_fma_f32 v[38:39], v[34:35], v[38:39], v[252:253]
	v_mfma_f32_16x16x4_f32 v[232:235], v156, v181, v[232:235]
	v_pk_fma_f32 v[252:253], v[36:37], v[38:39], v[202:203] op_sel:[0,1,0] op_sel_hi:[1,0,1] neg_lo:[1,0,0] neg_hi:[0,0,0]
	v_mfma_f32_16x16x4_f32 v[236:239], v156, v188, v[236:239]
	v_pk_fma_f32 v[38:39], v[34:35], v[38:39], v[252:253]
	v_mfma_f32_16x16x4_f32 v[240:243], v156, v189, v[240:243]
	ds_read_b128 v[192:195], v144 offset:49152
	s_waitcnt lgkmcnt(1)
	v_pk_fma_f32 v[252:253], v[36:37], v[38:39], v[244:245] op_sel:[0,1,0] op_sel_hi:[1,0,1] neg_lo:[1,0,0] neg_hi:[0,0,0]
	v_mfma_f32_16x16x4_f32 v[212:215], v157, v166, v[212:215]
	v_pk_fma_f32 v[38:39], v[34:35], v[38:39], v[252:253]
	v_mfma_f32_16x16x4_f32 v[216:219], v157, v167, v[216:219]
	v_pk_fma_f32 v[252:253], v[36:37], v[38:39], v[246:247] op_sel:[0,1,0] op_sel_hi:[1,0,1] neg_lo:[1,0,0] neg_hi:[0,0,0]
	v_mfma_f32_16x16x4_f32 v[220:223], v157, v174, v[220:223]
	v_pk_fma_f32 v[38:39], v[34:35], v[38:39], v[252:253]
	v_mfma_f32_16x16x4_f32 v[224:227], v157, v175, v[224:227]
	v_pk_fma_f32 v[252:253], v[36:37], v[38:39], v[248:249] op_sel:[0,1,0] op_sel_hi:[1,0,1] neg_lo:[1,0,0] neg_hi:[0,0,0]
	v_mfma_f32_16x16x4_f32 v[228:231], v157, v182, v[228:231]
	v_pk_fma_f32 v[38:39], v[34:35], v[38:39], v[252:253]
	v_mfma_f32_16x16x4_f32 v[232:235], v157, v183, v[232:235]
	v_pk_fma_f32 v[252:253], v[36:37], v[38:39], v[250:251] op_sel:[0,1,0] op_sel_hi:[1,0,1] neg_lo:[1,0,0] neg_hi:[0,0,0]
	v_mfma_f32_16x16x4_f32 v[236:239], v157, v190, v[236:239]
	v_pk_fma_f32 v[38:39], v[34:35], v[38:39], v[252:253]
	v_mfma_f32_16x16x4_f32 v[240:243], v157, v191, v[240:243]
	s_nop 9
	ds_write_b32 v145, v212
	ds_write_b32 v145, v213 offset:512
	ds_write_b32 v145, v214 offset:1024
	ds_write_b32 v145, v215 offset:1536
	ds_write_b32 v145, v216 offset:256
	ds_write_b32 v145, v217 offset:768
	ds_write_b32 v145, v218 offset:1280
	ds_write_b32 v145, v219 offset:1792
	ds_write_b32 v146, v220
	ds_write_b32 v146, v221 offset:512
	ds_write_b32 v146, v222 offset:1024
	ds_write_b32 v146, v223 offset:1536
	ds_write_b32 v146, v224 offset:256
	ds_write_b32 v146, v225 offset:768
	ds_write_b32 v146, v226 offset:1280
	ds_write_b32 v146, v227 offset:1792
	ds_write_b32 v147, v228
	ds_write_b32 v147, v229 offset:512
	ds_write_b32 v147, v230 offset:1024
	ds_write_b32 v147, v231 offset:1536
	ds_write_b32 v147, v232 offset:256
	ds_write_b32 v147, v233 offset:768
	ds_write_b32 v147, v234 offset:1280
	ds_write_b32 v147, v235 offset:1792
	ds_write_b32 v148, v236
	ds_write_b32 v148, v237 offset:512
	ds_write_b32 v148, v238 offset:1024
	ds_write_b32 v148, v239 offset:1536
	ds_write_b32 v148, v240 offset:256
	ds_write_b32 v148, v241 offset:768
	ds_write_b32 v148, v242 offset:1280
	ds_write_b32 v148, v243 offset:1792
	ds_read_b32 v196, v149
	ds_read_b32 v197, v149 offset:256
	ds_read_b32 v198, v149 offset:512
	ds_read_b32 v199, v149 offset:768
	ds_read_b32 v200, v149 offset:1024
	ds_read_b32 v201, v149 offset:1280
	ds_read_b32 v202, v149 offset:1536
	ds_read_b32 v203, v149 offset:1792
	ds_read_b32 v244, v150 offset:2048
	ds_read_b32 v245, v150 offset:2304
	ds_read_b32 v246, v150 offset:2560
	ds_read_b32 v247, v150 offset:2816
	ds_read_b32 v248, v150 offset:3072
	ds_read_b32 v249, v150 offset:3328
	ds_read_b32 v250, v150 offset:3584
	ds_read_b32 v251, v150 offset:3840
	s_waitcnt lgkmcnt(8)
	v_pk_fma_f32 v[252:253], v[36:37], v[38:39], v[196:197] op_sel:[0,1,0] op_sel_hi:[1,0,1] neg_lo:[1,0,0] neg_hi:[0,0,0]
	v_mfma_f32_16x16x4_f32 v[212:215], v192, v160, 0
	v_pk_fma_f32 v[38:39], v[34:35], v[38:39], v[252:253]
	v_mfma_f32_16x16x4_f32 v[216:219], v192, v161, 0
	v_pk_fma_f32 v[252:253], v[36:37], v[38:39], v[198:199] op_sel:[0,1,0] op_sel_hi:[1,0,1] neg_lo:[1,0,0] neg_hi:[0,0,0]
	v_mfma_f32_16x16x4_f32 v[220:223], v192, v168, 0
	v_pk_fma_f32 v[38:39], v[34:35], v[38:39], v[252:253]
	v_mfma_f32_16x16x4_f32 v[224:227], v192, v169, 0
	v_pk_fma_f32 v[252:253], v[36:37], v[38:39], v[200:201] op_sel:[0,1,0] op_sel_hi:[1,0,1] neg_lo:[1,0,0] neg_hi:[0,0,0]
	v_mfma_f32_16x16x4_f32 v[228:231], v192, v176, 0
	v_pk_fma_f32 v[38:39], v[34:35], v[38:39], v[252:253]
	v_mfma_f32_16x16x4_f32 v[232:235], v192, v177, 0
	v_pk_fma_f32 v[252:253], v[36:37], v[38:39], v[202:203] op_sel:[0,1,0] op_sel_hi:[1,0,1] neg_lo:[1,0,0] neg_hi:[0,0,0]
	v_mfma_f32_16x16x4_f32 v[236:239], v192, v184, 0
	v_pk_fma_f32 v[38:39], v[34:35], v[38:39], v[252:253]
	v_mfma_f32_16x16x4_f32 v[240:243], v192, v185, 0
	ds_read_b32 v196, v151 offset:4096
	ds_read_b32 v197, v151 offset:4352
	ds_read_b32 v198, v151 offset:4608
	ds_read_b32 v199, v151 offset:4864
	ds_read_b32 v200, v151 offset:5120
	ds_read_b32 v201, v151 offset:5376
	ds_read_b32 v202, v151 offset:5632
	ds_read_b32 v203, v151 offset:5888
	s_waitcnt lgkmcnt(8)
	v_pk_fma_f32 v[252:253], v[36:37], v[38:39], v[244:245] op_sel:[0,1,0] op_sel_hi:[1,0,1] neg_lo:[1,0,0] neg_hi:[0,0,0]
	v_mfma_f32_16x16x4_f32 v[212:215], v193, v162, v[212:215]
	v_pk_fma_f32 v[38:39], v[34:35], v[38:39], v[252:253]
	v_mfma_f32_16x16x4_f32 v[216:219], v193, v163, v[216:219]
	v_pk_fma_f32 v[252:253], v[36:37], v[38:39], v[246:247] op_sel:[0,1,0] op_sel_hi:[1,0,1] neg_lo:[1,0,0] neg_hi:[0,0,0]
	v_mfma_f32_16x16x4_f32 v[220:223], v193, v170, v[220:223]
	v_pk_fma_f32 v[38:39], v[34:35], v[38:39], v[252:253]
	v_mfma_f32_16x16x4_f32 v[224:227], v193, v171, v[224:227]
	v_pk_fma_f32 v[252:253], v[36:37], v[38:39], v[248:249] op_sel:[0,1,0] op_sel_hi:[1,0,1] neg_lo:[1,0,0] neg_hi:[0,0,0]
	v_mfma_f32_16x16x4_f32 v[228:231], v193, v178, v[228:231]
	v_pk_fma_f32 v[38:39], v[34:35], v[38:39], v[252:253]
	v_mfma_f32_16x16x4_f32 v[232:235], v193, v179, v[232:235]
	v_pk_fma_f32 v[252:253], v[36:37], v[38:39], v[250:251] op_sel:[0,1,0] op_sel_hi:[1,0,1] neg_lo:[1,0,0] neg_hi:[0,0,0]
	v_mfma_f32_16x16x4_f32 v[236:239], v193, v186, v[236:239]
	v_pk_fma_f32 v[38:39], v[34:35], v[38:39], v[252:253]
	v_mfma_f32_16x16x4_f32 v[240:243], v193, v187, v[240:243]
	ds_read_b32 v244, v152 offset:6144
	ds_read_b32 v245, v152 offset:6400
	ds_read_b32 v246, v152 offset:6656
	ds_read_b32 v247, v152 offset:6912
	ds_read_b32 v248, v152 offset:7168
	ds_read_b32 v249, v152 offset:7424
	ds_read_b32 v250, v152 offset:7680
	ds_read_b32 v251, v152 offset:7936
	s_waitcnt lgkmcnt(8)
	v_pk_fma_f32 v[252:253], v[36:37], v[38:39], v[196:197] op_sel:[0,1,0] op_sel_hi:[1,0,1] neg_lo:[1,0,0] neg_hi:[0,0,0]
	v_mfma_f32_16x16x4_f32 v[212:215], v194, v164, v[212:215]
	v_pk_fma_f32 v[38:39], v[34:35], v[38:39], v[252:253]
	v_mfma_f32_16x16x4_f32 v[216:219], v194, v165, v[216:219]
	v_pk_fma_f32 v[252:253], v[36:37], v[38:39], v[198:199] op_sel:[0,1,0] op_sel_hi:[1,0,1] neg_lo:[1,0,0] neg_hi:[0,0,0]
	v_mfma_f32_16x16x4_f32 v[220:223], v194, v172, v[220:223]
	v_pk_fma_f32 v[38:39], v[34:35], v[38:39], v[252:253]
	v_mfma_f32_16x16x4_f32 v[224:227], v194, v173, v[224:227]
	v_pk_fma_f32 v[252:253], v[36:37], v[38:39], v[200:201] op_sel:[0,1,0] op_sel_hi:[1,0,1] neg_lo:[1,0,0] neg_hi:[0,0,0]
	v_mfma_f32_16x16x4_f32 v[228:231], v194, v180, v[228:231]
	v_pk_fma_f32 v[38:39], v[34:35], v[38:39], v[252:253]
	v_mfma_f32_16x16x4_f32 v[232:235], v194, v181, v[232:235]
	v_pk_fma_f32 v[252:253], v[36:37], v[38:39], v[202:203] op_sel:[0,1,0] op_sel_hi:[1,0,1] neg_lo:[1,0,0] neg_hi:[0,0,0]
	v_mfma_f32_16x16x4_f32 v[236:239], v194, v188, v[236:239]
	v_pk_fma_f32 v[38:39], v[34:35], v[38:39], v[252:253]
	v_mfma_f32_16x16x4_f32 v[240:243], v194, v189, v[240:243]
	s_waitcnt lgkmcnt(0)
	v_pk_fma_f32 v[252:253], v[36:37], v[38:39], v[244:245] op_sel:[0,1,0] op_sel_hi:[1,0,1] neg_lo:[1,0,0] neg_hi:[0,0,0]
	v_mfma_f32_16x16x4_f32 v[212:215], v195, v166, v[212:215]
	v_pk_fma_f32 v[38:39], v[34:35], v[38:39], v[252:253]
	v_mfma_f32_16x16x4_f32 v[216:219], v195, v167, v[216:219]
	v_pk_fma_f32 v[252:253], v[36:37], v[38:39], v[246:247] op_sel:[0,1,0] op_sel_hi:[1,0,1] neg_lo:[1,0,0] neg_hi:[0,0,0]
	v_mfma_f32_16x16x4_f32 v[220:223], v195, v174, v[220:223]
	v_pk_fma_f32 v[38:39], v[34:35], v[38:39], v[252:253]
	v_mfma_f32_16x16x4_f32 v[224:227], v195, v175, v[224:227]
	v_pk_fma_f32 v[252:253], v[36:37], v[38:39], v[248:249] op_sel:[0,1,0] op_sel_hi:[1,0,1] neg_lo:[1,0,0] neg_hi:[0,0,0]
	v_mfma_f32_16x16x4_f32 v[228:231], v195, v182, v[228:231]
	v_pk_fma_f32 v[38:39], v[34:35], v[38:39], v[252:253]
	v_mfma_f32_16x16x4_f32 v[232:235], v195, v183, v[232:235]
	v_pk_fma_f32 v[252:253], v[36:37], v[38:39], v[250:251] op_sel:[0,1,0] op_sel_hi:[1,0,1] neg_lo:[1,0,0] neg_hi:[0,0,0]
	v_mfma_f32_16x16x4_f32 v[236:239], v195, v190, v[236:239]
	v_pk_fma_f32 v[38:39], v[34:35], v[38:39], v[252:253]
	v_mfma_f32_16x16x4_f32 v[240:243], v195, v191, v[240:243]
	s_nop 9
	ds_write_b32 v145, v212
	ds_write_b32 v145, v213 offset:512
	ds_write_b32 v145, v214 offset:1024
	ds_write_b32 v145, v215 offset:1536
	ds_write_b32 v145, v216 offset:256
	ds_write_b32 v145, v217 offset:768
	ds_write_b32 v145, v218 offset:1280
	ds_write_b32 v145, v219 offset:1792
	ds_write_b32 v146, v220
	ds_write_b32 v146, v221 offset:512
	ds_write_b32 v146, v222 offset:1024
	ds_write_b32 v146, v223 offset:1536
	ds_write_b32 v146, v224 offset:256
	ds_write_b32 v146, v225 offset:768
	ds_write_b32 v146, v226 offset:1280
	ds_write_b32 v146, v227 offset:1792
	ds_write_b32 v147, v228
	ds_write_b32 v147, v229 offset:512
	ds_write_b32 v147, v230 offset:1024
	ds_write_b32 v147, v231 offset:1536
	ds_write_b32 v147, v232 offset:256
	ds_write_b32 v147, v233 offset:768
	ds_write_b32 v147, v234 offset:1280
	ds_write_b32 v147, v235 offset:1792
	ds_write_b32 v148, v236
	ds_write_b32 v148, v237 offset:512
	ds_write_b32 v148, v238 offset:1024
	ds_write_b32 v148, v239 offset:1536
	ds_write_b32 v148, v240 offset:256
	ds_write_b32 v148, v241 offset:768
	ds_write_b32 v148, v242 offset:1280
	ds_write_b32 v148, v243 offset:1792
	ds_read_b32 v196, v149
	ds_read_b32 v197, v149 offset:256
	ds_read_b32 v198, v149 offset:512
	ds_read_b32 v199, v149 offset:768
	ds_read_b32 v200, v149 offset:1024
	ds_read_b32 v201, v149 offset:1280
	ds_read_b32 v202, v149 offset:1536
	ds_read_b32 v203, v149 offset:1792
	ds_read_b32 v244, v150 offset:2048
	ds_read_b32 v245, v150 offset:2304
	ds_read_b32 v246, v150 offset:2560
	ds_read_b32 v247, v150 offset:2816
	ds_read_b32 v248, v150 offset:3072
	ds_read_b32 v249, v150 offset:3328
	ds_read_b32 v250, v150 offset:3584
	ds_read_b32 v251, v150 offset:3840
	s_waitcnt lgkmcnt(8)
	v_pk_fma_f32 v[252:253], v[36:37], v[38:39], v[196:197] op_sel:[0,1,0] op_sel_hi:[1,0,1] neg_lo:[1,0,0] neg_hi:[0,0,0]
	s_nop 0
	v_pk_fma_f32 v[38:39], v[34:35], v[38:39], v[252:253]
	s_nop 0
	v_pk_fma_f32 v[252:253], v[36:37], v[38:39], v[198:199] op_sel:[0,1,0] op_sel_hi:[1,0,1] neg_lo:[1,0,0] neg_hi:[0,0,0]
	s_nop 0
	v_pk_fma_f32 v[38:39], v[34:35], v[38:39], v[252:253]
	s_nop 0
	v_pk_fma_f32 v[252:253], v[36:37], v[38:39], v[200:201] op_sel:[0,1,0] op_sel_hi:[1,0,1] neg_lo:[1,0,0] neg_hi:[0,0,0]
	s_nop 0
	v_pk_fma_f32 v[38:39], v[34:35], v[38:39], v[252:253]
	s_nop 0
	v_pk_fma_f32 v[252:253], v[36:37], v[38:39], v[202:203] op_sel:[0,1,0] op_sel_hi:[1,0,1] neg_lo:[1,0,0] neg_hi:[0,0,0]
	s_nop 0
	v_pk_fma_f32 v[38:39], v[34:35], v[38:39], v[252:253]
	s_nop 0
	ds_read_b32 v196, v151 offset:4096
	ds_read_b32 v197, v151 offset:4352
	ds_read_b32 v198, v151 offset:4608
	ds_read_b32 v199, v151 offset:4864
	ds_read_b32 v200, v151 offset:5120
	ds_read_b32 v201, v151 offset:5376
	ds_read_b32 v202, v151 offset:5632
	ds_read_b32 v203, v151 offset:5888
	s_waitcnt lgkmcnt(8)
	v_pk_fma_f32 v[252:253], v[36:37], v[38:39], v[244:245] op_sel:[0,1,0] op_sel_hi:[1,0,1] neg_lo:[1,0,0] neg_hi:[0,0,0]
	s_nop 0
	v_pk_fma_f32 v[38:39], v[34:35], v[38:39], v[252:253]
	s_nop 0
	v_pk_fma_f32 v[252:253], v[36:37], v[38:39], v[246:247] op_sel:[0,1,0] op_sel_hi:[1,0,1] neg_lo:[1,0,0] neg_hi:[0,0,0]
	s_nop 0
	v_pk_fma_f32 v[38:39], v[34:35], v[38:39], v[252:253]
	s_nop 0
	v_pk_fma_f32 v[252:253], v[36:37], v[38:39], v[248:249] op_sel:[0,1,0] op_sel_hi:[1,0,1] neg_lo:[1,0,0] neg_hi:[0,0,0]
	s_nop 0
	v_pk_fma_f32 v[38:39], v[34:35], v[38:39], v[252:253]
	s_nop 0
	v_pk_fma_f32 v[252:253], v[36:37], v[38:39], v[250:251] op_sel:[0,1,0] op_sel_hi:[1,0,1] neg_lo:[1,0,0] neg_hi:[0,0,0]
	s_nop 0
	v_pk_fma_f32 v[38:39], v[34:35], v[38:39], v[252:253]
	s_nop 0
	ds_read_b32 v244, v152 offset:6144
	ds_read_b32 v245, v152 offset:6400
	ds_read_b32 v246, v152 offset:6656
	ds_read_b32 v247, v152 offset:6912
	ds_read_b32 v248, v152 offset:7168
	ds_read_b32 v249, v152 offset:7424
	ds_read_b32 v250, v152 offset:7680
	ds_read_b32 v251, v152 offset:7936
	s_waitcnt lgkmcnt(8)
	v_pk_fma_f32 v[252:253], v[36:37], v[38:39], v[196:197] op_sel:[0,1,0] op_sel_hi:[1,0,1] neg_lo:[1,0,0] neg_hi:[0,0,0]
	s_nop 0
	v_pk_fma_f32 v[38:39], v[34:35], v[38:39], v[252:253]
	s_nop 0
	v_pk_fma_f32 v[252:253], v[36:37], v[38:39], v[198:199] op_sel:[0,1,0] op_sel_hi:[1,0,1] neg_lo:[1,0,0] neg_hi:[0,0,0]
	s_nop 0
	v_pk_fma_f32 v[38:39], v[34:35], v[38:39], v[252:253]
	s_nop 0
	v_pk_fma_f32 v[252:253], v[36:37], v[38:39], v[200:201] op_sel:[0,1,0] op_sel_hi:[1,0,1] neg_lo:[1,0,0] neg_hi:[0,0,0]
	s_nop 0
	v_pk_fma_f32 v[38:39], v[34:35], v[38:39], v[252:253]
	s_nop 0
	v_pk_fma_f32 v[252:253], v[36:37], v[38:39], v[202:203] op_sel:[0,1,0] op_sel_hi:[1,0,1] neg_lo:[1,0,0] neg_hi:[0,0,0]
	s_nop 0
	v_pk_fma_f32 v[38:39], v[34:35], v[38:39], v[252:253]
	s_nop 0
	s_waitcnt lgkmcnt(0)
	v_pk_fma_f32 v[252:253], v[36:37], v[38:39], v[244:245] op_sel:[0,1,0] op_sel_hi:[1,0,1] neg_lo:[1,0,0] neg_hi:[0,0,0]
	s_nop 0
	v_pk_fma_f32 v[38:39], v[34:35], v[38:39], v[252:253]
	s_nop 0
	v_pk_fma_f32 v[252:253], v[36:37], v[38:39], v[246:247] op_sel:[0,1,0] op_sel_hi:[1,0,1] neg_lo:[1,0,0] neg_hi:[0,0,0]
	s_nop 0
	v_pk_fma_f32 v[38:39], v[34:35], v[38:39], v[252:253]
	s_nop 0
	v_pk_fma_f32 v[252:253], v[36:37], v[38:39], v[248:249] op_sel:[0,1,0] op_sel_hi:[1,0,1] neg_lo:[1,0,0] neg_hi:[0,0,0]
	s_nop 0
	v_pk_fma_f32 v[38:39], v[34:35], v[38:39], v[252:253]
	s_nop 0
	v_pk_fma_f32 v[252:253], v[36:37], v[38:39], v[250:251] op_sel:[0,1,0] op_sel_hi:[1,0,1] neg_lo:[1,0,0] neg_hi:[0,0,0]
	s_nop 0
	v_pk_fma_f32 v[38:39], v[34:35], v[38:39], v[252:253]
	s_nop 0
	s_lshl_b64 s[10:11], s[44:45], 9
	v_lshl_add_u64 v[32:33], v[30:31], 0, s[10:11]
	s_mov_b32 s10, 8
	s_mov_b64 s[46:47], 0
	s_and_b64 vcc, exec, s[12:13]
	global_store_dwordx2 v[32:33], v[38:39], off
	s_cbranch_vccz .LBB0_2205
	v_add_u32_e32 v30, s18, v70
	v_ashrrev_i32_e32 v31, 31, v30
	v_lshlrev_b64 v[32:33], 10, v[30:31]
	v_lshl_add_u64 v[32:33], v[8:9], 0, v[32:33]
	s_barrier
	global_load_ushort v108, v[32:33], off
	v_and_b32_e32 v29, 0x1fe0, v30
	v_cmp_ne_u32_e32 vcc, 0, v29
	v_mov_b32_e32 v110, 0
	s_and_saveexec_b64 s[10:11], vcc
	s_cbranch_execz .LBB0_2218
	global_load_ushort v1, v[32:33], off offset:-512
	s_waitcnt vmcnt(0)
	v_cvt_f32_f16_e32 v110, v1
